# static s_setprio 1 for the younger GEMM half (waves 4-7) outside P7; P7 keeps waves 0-3 raised
# baseline (speedup 1.0000x reference)
_Z3fwd4Args:
	s_mov_b32 s86, s2
	s_load_dwordx8 s[60:67], s[0:1], 0x80
	s_load_dword s88, s[0:1], 0xc0
	s_load_dwordx4 s[80:83], s[0:1], 0xa0
	s_load_dwordx2 s[70:71], s[0:1], 0xb0
	s_add_u32 s2, s0, 0xc0
	s_addc_u32 s3, s1, 0
	v_readfirstlane_b32 s87, v0
	s_nop 3
	s_cmp_lt_u32 s87, 0x100
	s_cbranch_scc1 .Lstatic_prio_skip
	s_setprio 1
.Lstatic_prio_skip:
	v_writelane_b32 v254, s2, 0
	s_mov_b32 s4, 0
	s_nop 0
	v_writelane_b32 v254, s3, 1
	s_waitcnt lgkmcnt(0)
	s_and_b32 s2, s88, 7
	s_cmp_lg_u32 s2, 0
	s_mov_b32 s2, s86
	s_cbranch_scc1 .LBB0_2
	s_ashr_i32 s3, s86, 31
	s_lshr_b32 s3, s3, 29
	s_add_i32 s3, s86, s3
	s_ashr_i32 s5, s3, 3
	s_and_b32 s3, s3, -8
	s_ashr_i32 s2, s88, 3
	s_sub_i32 s3, s86, s3
	s_mul_i32 s2, s2, s3
	s_add_i32 s2, s2, s5

.LBB0_720:
	v_writelane_b32 v254, s80, 53
	s_cmp_lt_i32 s70, 8
	s_cselect_b64 s[0:1], -1, 0
	v_writelane_b32 v254, s81, 54
	v_writelane_b32 v254, s82, 55
	v_writelane_b32 v254, s83, 56
	s_and_b64 s[0:1], s[0:1], s[4:5]
	v_writelane_b32 v254, s0, 57
	s_andn2_b64 vcc, exec, s[0:1]
	s_nop 0
	v_writelane_b32 v254, s1, 58
	s_cbranch_vccnz .LBB0_772
	s_cmp_ge_u32 s87, 0x100
	s_cbranch_scc1 .Lp7_prio_hi
	s_setprio 1
	s_branch .Lp7_prio_skip
.Lp7_prio_hi:
	s_setprio 0
.Lp7_prio_skip:
	v_writelane_b32 v254, s72, 59
	v_lshlrev_b32_e32 v1, 2, v212
	s_and_b32 s85, s87, 0xffffffc0
	v_writelane_b32 v254, s73, 60
	v_writelane_b32 v255, s86, 0
	v_readlane_b32 s0, v254, 2
	v_readlane_b32 s6, v254, 8
	v_readlane_b32 s7, v254, 9
	v_readlane_b32 s8, v254, 10
	v_readlane_b32 s9, v254, 11
	v_readlane_b32 s10, v254, 12
	v_readlane_b32 s11, v254, 13
	v_readlane_b32 s12, v254, 14
	v_readlane_b32 s13, v254, 15
	global_load_dword v2, v1, s[6:7]
	s_waitcnt lgkmcnt(0)
	global_load_dword v3, v1, s[8:9]
	global_load_dword v4, v1, s[6:7] offset:256
	global_load_dword v5, v1, s[8:9] offset:256
	global_load_dword v6, v1, s[10:11] offset:256
	global_load_dword v7, v1, s[12:13] offset:256
	global_load_dword v8, v1, s[10:11]
	global_load_dword v9, v1, s[12:13]
	v_mbcnt_lo_u32_b32 v1, -1, 0
	v_mbcnt_hi_u32_b32 v1, -1, v1
	v_and_b32_e32 v10, 64, v1
	v_xor_b32_e32 v11, 1, v1
	v_add_u32_e32 v10, 64, v10
	v_cmp_lt_i32_e32 vcc, v11, v10
	v_xor_b32_e32 v12, 2, v1
	v_xor_b32_e32 v13, 4, v1
	v_cndmask_b32_e32 v11, v1, v11, vcc
	v_lshlrev_b32_e32 v11, 2, v11
	v_cmp_lt_i32_e32 vcc, v12, v10
	v_xor_b32_e32 v14, 8, v1
	v_xor_b32_e32 v15, 16, v1
	v_xor_b32_e32 v16, 32, v1
	v_readlane_b32 s2, v254, 4
	v_readlane_b32 s2, v254, 26
	s_lshl_b32 s0, s2, 8
	v_readlane_b32 s1, v254, 3
	s_add_i32 s0, s0, 0
	s_lshl_b32 s1, s2, 10
	s_add_i32 s0, s0, 0x20000
	v_readlane_b32 s3, v254, 5
	v_readlane_b32 s4, v254, 6
	v_readlane_b32 s5, v254, 7
	v_readlane_b32 s14, v254, 16
	v_readlane_b32 s15, v254, 17
	s_add_i32 s1, s1, 0
	v_writelane_b32 v254, s0, 61
	s_lshl_b32 s0, s2, 14
	v_writelane_b32 v254, s1, 62
	s_add_i32 s70, s1, 0x10000
	s_add_i32 s0, s0, 0
	v_writelane_b32 v254, s0, 63
	s_cmpk_gt_i32 s86, 0x2ff
	s_waitcnt vmcnt(0)
	v_mul_f32_e32 v4, v4, v5
	v_fmac_f32_e32 v4, v2, v3
	v_mul_f32_e32 v5, v6, v7
	ds_bpermute_b32 v2, v11, v4
	v_fmac_f32_e32 v5, v8, v9
	ds_bpermute_b32 v3, v11, v5
	v_cndmask_b32_e32 v6, v1, v12, vcc
	v_lshlrev_b32_e32 v6, 2, v6
	s_waitcnt lgkmcnt(1)
	v_add_f32_e32 v2, v4, v2
	ds_bpermute_b32 v4, v6, v2
	s_waitcnt lgkmcnt(1)
	v_add_f32_e32 v3, v5, v3
	ds_bpermute_b32 v5, v6, v3
	v_cmp_lt_i32_e32 vcc, v13, v10
	s_waitcnt lgkmcnt(1)
	v_add_f32_e32 v2, v2, v4
	v_cndmask_b32_e32 v6, v1, v13, vcc
	v_lshlrev_b32_e32 v6, 2, v6
	s_waitcnt lgkmcnt(0)
	v_add_f32_e32 v3, v3, v5
	ds_bpermute_b32 v4, v6, v2
	ds_bpermute_b32 v5, v6, v3
	v_cmp_lt_i32_e32 vcc, v14, v10
	s_waitcnt lgkmcnt(1)
	v_add_f32_e32 v2, v2, v4
	v_cndmask_b32_e32 v6, v1, v14, vcc
	v_lshlrev_b32_e32 v6, 2, v6
	s_waitcnt lgkmcnt(0)
	v_add_f32_e32 v3, v3, v5
	ds_bpermute_b32 v4, v6, v2
	ds_bpermute_b32 v5, v6, v3
	v_cmp_lt_i32_e32 vcc, v15, v10
	s_waitcnt lgkmcnt(1)
	v_add_f32_e32 v2, v2, v4
	v_cndmask_b32_e32 v6, v1, v15, vcc
	v_lshlrev_b32_e32 v213, 2, v6
	s_waitcnt lgkmcnt(0)
	v_add_f32_e32 v3, v3, v5
	ds_bpermute_b32 v4, v213, v2
	ds_bpermute_b32 v5, v213, v3
	v_cmp_lt_i32_e32 vcc, v16, v10
	s_waitcnt lgkmcnt(1)
	v_add_f32_e32 v2, v2, v4
	v_cndmask_b32_e32 v1, v1, v16, vcc
	v_lshlrev_b32_e32 v1, 2, v1
	s_waitcnt lgkmcnt(0)
	v_add_f32_e32 v3, v3, v5
	ds_bpermute_b32 v4, v1, v2
	ds_bpermute_b32 v5, v1, v3
	s_cbranch_scc1 .LBB0_766
	s_lshr_b32 s0, s87, 8
	s_bfe_u32 s1, s87, 0x20006
	s_lshl_b32 s2, s0, 14
	s_lshl_b32 s3, s1, 5
	s_add_i32 s2, s2, 0
	s_lshl_b32 s1, s1, 1
	s_lshl_b32 s20, s0, 7
	v_writelane_b32 v255, s2, 1
	s_add_i32 s2, s1, s0
	s_xor_b32 s0, s0, 1
	s_add_i32 s1, s1, s0
	s_lshl_b32 s2, s2, 14
	s_lshl_b32 s0, s1, 14
	s_add_i32 s2, s2, 0
	s_add_i32 s0, s0, 0
	v_writelane_b32 v255, s2, 2
	s_cmpk_lt_u32 s87, 0x100
	v_writelane_b32 v255, s0, 3
	s_cselect_b64 s[36:37], -1, 0
	s_and_b32 s0, s20, 0x80
	v_writelane_b32 v255, s0, 4
	s_xor_b32 s0, s85, 0x100
	s_lshl_b32 s0, s0, 2
	s_waitcnt lgkmcnt(1)
	v_add_f32_e32 v1, v2, v4
	s_waitcnt lgkmcnt(0)
	v_add_f32_e32 v2, v3, v5
	s_add_i32 s0, s0, 0
	v_mul_f32_e32 v1, 0x3fb8aa3b, v1
	v_mul_f32_e32 v2, 0x3fb8aa3b, v2
	s_add_i32 s0, s0, 0x20000
	v_exp_f32_e32 v1, v1
	v_exp_f32_e32 v2, v2
	v_writelane_b32 v255, s0, 5
	v_writelane_b32 v255, s3, 6
	s_sub_i32 s0, s3, 64
	v_writelane_b32 v255, s0, 7
	s_add_i32 s0, 0, 0x8000
	v_writelane_b32 v255, s0, 8
	v_sub_f32_e32 v1, v1, v2
	v_readlane_b32 s0, v255, 0
	v_writelane_b32 v255, s90, 9
	v_add_f32_e32 v210, 0x3eb60549, v1
	v_mov_b32_e32 v211, v210
	v_writelane_b32 v255, s91, 10
	s_movk_i32 s2, 0xf0
	v_mov_b32_e32 v3, 0
	s_mov_b32 s97, 0x3e0293ee
	s_mov_b32 s80, 0x40c00000
	s_mov_b32 s81, 0x42000000
	s_mov_b32 s82, 0x40400000
	s_mov_b32 s83, 0x41000000
	s_mov_b32 s92, 0x41100000
	s_mov_b32 s93, 0x41200000
	s_mov_b32 s77, 0x41300000
	s_mov_b32 s84, 0x41800000
	s_mov_b32 s33, 0x41880000
	s_mov_b32 s73, 0x41900000
	s_mov_b32 s96, 0x41980000
	s_mov_b32 s86, 0x41c00000
	s_mov_b32 s78, 0x41c80000
	s_mov_b32 s79, 0x41d00000
	s_mov_b32 s87, 0x41d80000
	v_mov_b32_e32 v214, 0x3727c5ac
	v_mov_b32_e32 v215, 0xff800000
	s_mov_b32 s7, s0
	v_writelane_b32 v255, s20, 11
	s_branch .LBB0_724

.LBB0_772:
	s_setprio 0
	v_cmp_gt_u32_e32 vcc, 0x100, v0
	s_cbranch_vccnz .Lp7x_prio_skip
	s_setprio 1
